# P8 stagger regrouped: first (undelayed) group shrunk to 2 of 8 pm-slots so the three-tile workgroups burst with fewer neighbours; delays 0/8.5/17.5us
# speedup vs baseline: 1.0004x; 1.0004x over previous
.LBB0_1115:
	v_readlane_b32 s0, v246, 4
	v_readlane_b32 s1, v246, 5
	s_cmp_lt_i32 s0, 9
	s_cselect_b64 s[0:1], -1, 0
	s_and_b64 s[2:3], s[0:1], s[2:3]
	s_andn2_b64 vcc, exec, s[2:3]
	s_cbranch_vccnz .LBB0_1150
	s_bfe_u32 s8, s30, 0x30003
	s_cmp_lt_u32 s8, 2
	s_cbranch_scc1 .Lstg8_done
	s_sleep 127
	s_sleep 127
	s_sleep 20
	s_cmp_lt_u32 s8, 5
	s_cbranch_scc1 .Lstg8_done
	s_sleep 127
	s_sleep 127
	s_sleep 40
